# GEMM in-loop LDS-DMA issue blocks (in-proj, merge x2, out-proj, peer_q): M0 formed with SALU adds from one readfirstlane instead of 8 VALU add + readfirstlane pairs
# speedup vs baseline: 1.0049x; 1.0018x over previous
; template <bool SW>
; __device__ __forceinline__ void gemm_mainloop(const bf16_t* __restrict__ A, int lda, const bf16_t* __restrict__ Bt, int ldb, int K,
;                                               f32x16 (&acc)[2][2], char* lds, int kstart) {
;     ...
;     if (more) {
;       char* d = ldst + ((kt + 1) & 1) * GEMM_BUF;
;       const int ko = ((kt + 1 + kstart) & (nk - 1)) * 64;
; #pragma unroll
;       for (int i = 0; i < 4; ++i) { glds16(ap[i] + ko, d + i * 1024); glds16(bp[i] + ko, d + 16384 + i * 1024); }
;     }
.LBB0_178:
	s_andn2_b64 vcc, exec, s[0:1]
	s_cbranch_vccnz .LBB0_175
	s_add_i32 s35, s34, 0x8000
	s_and_b32 s0, s35, 0x8000
	v_readfirstlane_b32 s1, v147
	s_and_b32 s76, s2, 0x3c0
	s_lshl_b32 s76, s76, 1
	s_add_i32 s0, s0, s1
	s_mov_b32 m0, s0
	v_lshl_add_u64 v[138:139], v[116:117], 0, s[76:77]
	global_load_lds_dwordx4 v[138:139], off
	s_add_i32 m0, s0, 0x4000
	v_lshl_add_u64 v[138:139], v[130:131], 0, s[76:77]
	global_load_lds_dwordx4 v[138:139], off
	s_add_i32 m0, s0, 0x400
	v_lshl_add_u64 v[138:139], v[118:119], 0, s[76:77]
	global_load_lds_dwordx4 v[138:139], off
	s_add_i32 m0, s0, 0x4400
	v_lshl_add_u64 v[138:139], v[132:133], 0, s[76:77]
	global_load_lds_dwordx4 v[138:139], off
	s_add_i32 m0, s0, 0x800
	v_lshl_add_u64 v[138:139], v[120:121], 0, s[76:77]
	global_load_lds_dwordx4 v[138:139], off
	s_add_i32 m0, s0, 0x4800
	v_lshl_add_u64 v[138:139], v[134:135], 0, s[76:77]
	global_load_lds_dwordx4 v[138:139], off
	s_add_i32 m0, s0, 0xc00
	v_lshl_add_u64 v[138:139], v[122:123], 0, s[76:77]
	global_load_lds_dwordx4 v[138:139], off
	s_add_i32 m0, s0, 0x4c00
	v_lshl_add_u64 v[138:139], v[136:137], 0, s[76:77]
	global_load_lds_dwordx4 v[138:139], off
	s_branch .LBB0_175

; template <bool SW>
; __device__ __forceinline__ void gemm_mainloop(const bf16_t* __restrict__ A, int lda, const bf16_t* __restrict__ Bt, int ldb, int K,
;                                               f32x16 (&acc)[2][2], char* lds, int kstart) {
;     ...
;     if (more) {
;       char* d = ldst + ((kt + 1) & 1) * GEMM_BUF;
;       const int ko = ((kt + 1 + kstart) & (nk - 1)) * 64;
; #pragma unroll
;       for (int i = 0; i < 4; ++i) { glds16(ap[i] + ko, d + i * 1024); glds16(bp[i] + ko, d + 16384 + i * 1024); }
;     }
.LBB0_266:
	s_andn2_b64 vcc, exec, s[0:1]
	s_cbranch_vccnz .LBB0_263
	s_add_i32 s35, s34, 0x8000
	s_and_b32 s0, s35, 0x8000
	v_readfirstlane_b32 s1, v147
	s_and_b32 s76, s2, 0x3c0
	s_lshl_b32 s76, s76, 1
	s_add_i32 s0, s0, s1
	s_mov_b32 m0, s0
	v_lshl_add_u64 v[124:125], v[116:117], 0, s[76:77]
	global_load_lds_dwordx4 v[124:125], off
	s_add_i32 m0, s0, 0x4000
	v_lshl_add_u64 v[124:125], v[130:131], 0, s[76:77]
	global_load_lds_dwordx4 v[124:125], off
	s_add_i32 m0, s0, 0x400
	v_lshl_add_u64 v[124:125], v[118:119], 0, s[76:77]
	global_load_lds_dwordx4 v[124:125], off
	s_add_i32 m0, s0, 0x4400
	v_lshl_add_u64 v[124:125], v[132:133], 0, s[76:77]
	global_load_lds_dwordx4 v[124:125], off
	s_add_i32 m0, s0, 0x800
	v_lshl_add_u64 v[124:125], v[120:121], 0, s[76:77]
	global_load_lds_dwordx4 v[124:125], off
	s_add_i32 m0, s0, 0x4800
	v_lshl_add_u64 v[124:125], v[134:135], 0, s[76:77]
	global_load_lds_dwordx4 v[124:125], off
	s_add_i32 m0, s0, 0xc00
	v_lshl_add_u64 v[124:125], v[122:123], 0, s[76:77]
	global_load_lds_dwordx4 v[124:125], off
	s_add_i32 m0, s0, 0x4c00
	v_lshl_add_u64 v[124:125], v[136:137], 0, s[76:77]
	global_load_lds_dwordx4 v[124:125], off
	s_branch .LBB0_263

; template <bool SW>
; __device__ __forceinline__ void gemm_mainloop(const bf16_t* __restrict__ A, int lda, const bf16_t* __restrict__ Bt, int ldb, int K,
;                                               f32x16 (&acc)[2][2], char* lds, int kstart) {
;     ...
;     if (more) {
;       char* d = ldst + ((kt + 1) & 1) * GEMM_BUF;
;       const int ko = ((kt + 1 + kstart) & (nk - 1)) * 64;
; #pragma unroll
;       for (int i = 0; i < 4; ++i) { glds16(ap[i] + ko, d + i * 1024); glds16(bp[i] + ko, d + 16384 + i * 1024); }
;     }
.LBB0_792:
	s_andn2_b64 vcc, exec, s[0:1]
	s_cbranch_vccnz .LBB0_789
	s_add_i32 s48, s47, 0x8000
	s_and_b32 s0, s48, 0x8000
	v_readfirstlane_b32 s1, v102
	s_and_b32 s10, s45, 0x3c0
	s_lshl_b32 s10, s10, 1
	s_add_i32 s0, s0, s1
	s_mov_b32 m0, s0
	v_lshl_add_u64 v[100:101], v[84:85], 0, s[10:11]
	global_load_lds_dwordx4 v[100:101], off
	s_add_i32 m0, s0, 0x4000
	v_lshl_add_u64 v[100:101], v[86:87], 0, s[10:11]
	global_load_lds_dwordx4 v[100:101], off
	s_add_i32 m0, s0, 0x400
	v_lshl_add_u64 v[100:101], v[88:89], 0, s[10:11]
	global_load_lds_dwordx4 v[100:101], off
	s_add_i32 m0, s0, 0x4400
	v_lshl_add_u64 v[100:101], v[90:91], 0, s[10:11]
	global_load_lds_dwordx4 v[100:101], off
	s_add_i32 m0, s0, 0x800
	v_lshl_add_u64 v[100:101], v[92:93], 0, s[10:11]
	global_load_lds_dwordx4 v[100:101], off
	s_add_i32 m0, s0, 0x4800
	v_lshl_add_u64 v[100:101], v[94:95], 0, s[10:11]
	global_load_lds_dwordx4 v[100:101], off
	s_add_i32 m0, s0, 0xc00
	v_lshl_add_u64 v[100:101], v[96:97], 0, s[10:11]
	global_load_lds_dwordx4 v[100:101], off
	s_add_i32 m0, s0, 0x4c00
	v_lshl_add_u64 v[100:101], v[98:99], 0, s[10:11]
	global_load_lds_dwordx4 v[100:101], off
	s_branch .LBB0_789

; template <bool SW>
; __device__ __forceinline__ void gemm_mainloop(const bf16_t* __restrict__ A, int lda, const bf16_t* __restrict__ Bt, int ldb, int K,
;                                               f32x16 (&acc)[2][2], char* lds, int kstart) {
;     ...
;     if (more) {
;       char* d = ldst + ((kt + 1) & 1) * GEMM_BUF;
;       const int ko = ((kt + 1 + kstart) & (nk - 1)) * 64;
; #pragma unroll
;       for (int i = 0; i < 4; ++i) { glds16(ap[i] + ko, d + i * 1024); glds16(bp[i] + ko, d + 16384 + i * 1024); }
;     }
.LBB0_798:
	s_andn2_b64 vcc, exec, s[0:1]
	s_cbranch_vccnz .LBB0_795
	s_add_i32 s40, s39, 0x8000
	s_and_b32 s0, s40, 0x8000
	v_readfirstlane_b32 s1, v102
	s_and_b32 s10, s42, 0x3c0
	s_lshl_b32 s10, s10, 1
	s_add_i32 s0, s0, s1
	s_mov_b32 m0, s0
	v_lshl_add_u64 v[118:119], v[86:87], 0, s[10:11]
	global_load_lds_dwordx4 v[118:119], off
	s_add_i32 m0, s0, 0x4000
	v_lshl_add_u64 v[118:119], v[88:89], 0, s[10:11]
	global_load_lds_dwordx4 v[118:119], off
	s_add_i32 m0, s0, 0x400
	v_lshl_add_u64 v[118:119], v[90:91], 0, s[10:11]
	global_load_lds_dwordx4 v[118:119], off
	s_add_i32 m0, s0, 0x4400
	v_lshl_add_u64 v[118:119], v[92:93], 0, s[10:11]
	global_load_lds_dwordx4 v[118:119], off
	s_add_i32 m0, s0, 0x800
	v_lshl_add_u64 v[118:119], v[94:95], 0, s[10:11]
	global_load_lds_dwordx4 v[118:119], off
	s_add_i32 m0, s0, 0x4800
	v_lshl_add_u64 v[118:119], v[96:97], 0, s[10:11]
	global_load_lds_dwordx4 v[118:119], off
	s_add_i32 m0, s0, 0xc00
	v_lshl_add_u64 v[118:119], v[98:99], 0, s[10:11]
	global_load_lds_dwordx4 v[118:119], off
	s_add_i32 m0, s0, 0x4c00
	v_lshl_add_u64 v[118:119], v[100:101], 0, s[10:11]
	global_load_lds_dwordx4 v[118:119], off
	s_branch .LBB0_795

; template <bool SW>
; __device__ __forceinline__ void gemm_mainloop(const bf16_t* __restrict__ A, int lda, const bf16_t* __restrict__ Bt, int ldb, int K,
;                                               f32x16 (&acc)[2][2], char* lds, int kstart) {
;     ...
;     if (more) {
;       char* d = ldst + ((kt + 1) & 1) * GEMM_BUF;
;       const int ko = ((kt + 1 + kstart) & (nk - 1)) * 64;
; #pragma unroll
;       for (int i = 0; i < 4; ++i) { glds16(ap[i] + ko, d + i * 1024); glds16(bp[i] + ko, d + 16384 + i * 1024); }
;     }
.LBB0_874:
	s_andn2_b64 vcc, exec, s[0:1]
	s_cbranch_vccnz .LBB0_871
	s_add_i32 s42, s41, 0x8000
	s_and_b32 s0, s42, 0x8000
	v_readfirstlane_b32 s1, v97
	s_and_b32 s12, s39, 0x3c0
	s_lshl_b32 s12, s12, 1
	s_add_i32 s0, s0, s1
	s_mov_b32 m0, s0
	v_lshl_add_u64 v[112:113], v[80:81], 0, s[12:13]
	global_load_lds_dwordx4 v[112:113], off
	s_add_i32 m0, s0, 0x4000
	v_lshl_add_u64 v[112:113], v[82:83], 0, s[12:13]
	global_load_lds_dwordx4 v[112:113], off
	s_add_i32 m0, s0, 0x400
	v_lshl_add_u64 v[112:113], v[84:85], 0, s[12:13]
	global_load_lds_dwordx4 v[112:113], off
	s_add_i32 m0, s0, 0x4400
	v_lshl_add_u64 v[112:113], v[86:87], 0, s[12:13]
	global_load_lds_dwordx4 v[112:113], off
	s_add_i32 m0, s0, 0x800
	v_lshl_add_u64 v[112:113], v[88:89], 0, s[12:13]
	global_load_lds_dwordx4 v[112:113], off
	s_add_i32 m0, s0, 0x4800
	v_lshl_add_u64 v[112:113], v[90:91], 0, s[12:13]
	global_load_lds_dwordx4 v[112:113], off
	s_add_i32 m0, s0, 0xc00
	v_lshl_add_u64 v[112:113], v[92:93], 0, s[12:13]
	global_load_lds_dwordx4 v[112:113], off
	s_add_i32 m0, s0, 0x4c00
	v_lshl_add_u64 v[112:113], v[94:95], 0, s[12:13]
	global_load_lds_dwordx4 v[112:113], off
	s_branch .LBB0_871

; template <bool SW>
; __device__ __forceinline__ void gemm_mainloop(const bf16_t* __restrict__ A, int lda, const bf16_t* __restrict__ Bt, int ldb, int K,
;                                               f32x16 (&acc)[2][2], char* lds, int kstart) {
;     ...
;     if (more) {
;       char* d = ldst + ((kt + 1) & 1) * GEMM_BUF;
;       const int ko = ((kt + 1 + kstart) & (nk - 1)) * 64;
; #pragma unroll
;       for (int i = 0; i < 4; ++i) { glds16(ap[i] + ko, d + i * 1024); glds16(bp[i] + ko, d + 16384 + i * 1024); }
;     }
.LBB0_1023:
	s_andn2_b64 vcc, exec, s[0:1]
	s_cbranch_vccnz .LBB0_1020
	s_add_i32 s41, s40, 0x8000
	s_and_b32 s0, s41, 0x8000
	v_readfirstlane_b32 s1, v99
	s_and_b32 s14, s38, 0x3c0
	s_lshl_b32 s14, s14, 1
	s_add_i32 s0, s0, s1
	s_mov_b32 m0, s0
	v_lshl_add_u64 v[114:115], v[82:83], 0, s[14:15]
	global_load_lds_dwordx4 v[114:115], off
	s_add_i32 m0, s0, 0x4000
	v_lshl_add_u64 v[114:115], v[84:85], 0, s[14:15]
	global_load_lds_dwordx4 v[114:115], off
	s_add_i32 m0, s0, 0x400
	v_lshl_add_u64 v[114:115], v[86:87], 0, s[14:15]
	global_load_lds_dwordx4 v[114:115], off
	s_add_i32 m0, s0, 0x4400
	v_lshl_add_u64 v[114:115], v[88:89], 0, s[14:15]
	global_load_lds_dwordx4 v[114:115], off
	s_add_i32 m0, s0, 0x800
	v_lshl_add_u64 v[114:115], v[90:91], 0, s[14:15]
	global_load_lds_dwordx4 v[114:115], off
	s_add_i32 m0, s0, 0x4800
	v_lshl_add_u64 v[114:115], v[92:93], 0, s[14:15]
	global_load_lds_dwordx4 v[114:115], off
	s_add_i32 m0, s0, 0xc00
	v_lshl_add_u64 v[114:115], v[94:95], 0, s[14:15]
	global_load_lds_dwordx4 v[114:115], off
	s_add_i32 m0, s0, 0x4c00
	v_lshl_add_u64 v[114:115], v[96:97], 0, s[14:15]
	global_load_lds_dwordx4 v[114:115], off
	s_branch .LBB0_1020
